# ret_gate loop loads issued together, ret/hgrn scan loops batched (8 loads in flight)
# speedup vs baseline: 1.0054x; 1.0054x over previous
; __device__ __forceinline__ unsigned cvt_pk_bf16(float lo, float hi) { const f32v2_t v = {lo, hi}; const bf16v2_t r = __builtin_convertvector(v, bf16v2_t); return __builtin_bit_cast(unsigned, r); }
; __device__ __forceinline__ float bflo(unsigned u) { return __uint_as_float(u << 16); }
; __device__ __forceinline__ float bfhi(unsigned u) { return __uint_as_float(u & 0xffff0000u); }
; __device__ __forceinline__ float siluf_(float x) { return x * __builtin_amdgcn_rcpf(1.f + __expf(-x)); }
; __device__ __forceinline__ void pass_ret_gate(const Params& P, int half) {
;     ...
;     for (size_t i = GTID; i < n8; i += GTHREADS) {
;         const int t = (int)(i >> 9), c = (int)(i & 511) * 8, h = c >> 9;
;         const float rs = rsqrtf(rssq[t * 8 + h] * (1.f / 512.f) + EPS);
;         u32x4 o = *(u32x4*)(OB + (size_t)t * 4096 + c); const u32x4 g = *(const u32x4*)(Z + (size_t)t * ODD_IN + 8192 + c);
; #pragma unroll
;         for (int j = 0; j < 4; ++j) o[j] = cvt_pk_bf16(bflo(o[j]) * rs * siluf_(bflo(g[j])), bfhi(o[j]) * rs * siluf_(bfhi(g[j])));
;         *(u32x4*)(OB + (size_t)t * 4096 + c) = o;
;     }
.LBB0_44:
	v_alignbit_b32 v3, v1, v0, 9
	v_bfe_u32 v6, v2, 9, 3
	v_lshl_or_b32 v180, v3, 3, v6
	v_lshl_add_u64 v[6:7], v[180:181], 2, s[20:21]
	global_load_dword v13, v[6:7], off
	v_and_b32_e32 v8, 0xff8, v2
	v_lshlrev_b32_e32 v180, 1, v8
	v_mov_b64_e32 v[8:9], s[92:93]
	v_lshrrev_b64 v[4:5], 9, v[0:1]
	v_mad_u64_u32 v[8:9], s[2:3], v3, s16, v[8:9]
	v_lshlrev_b64 v[4:5], 13, v[4:5]
	v_lshl_add_u64 v[8:9], v[8:9], 0, v[180:181]
	s_mov_b32 s2, 0x19c04000
	v_lshl_add_u64 v[4:5], s[86:87], 0, v[4:5]
	s_waitcnt lgkmcnt(0)
	v_lshl_add_u64 v[14:15], v[4:5], 0, v[180:181]
	v_lshl_add_u64 v[0:1], v[0:1], 0, s[68:69]
	v_add_u32_e32 v2, s22, v2
	v_add_co_u32_e32 v8, vcc, s2, v8
	s_nop 1
	v_addc_co_u32_e32 v9, vcc, 0, v9, vcc
	global_load_dwordx4 v[4:7], v[14:15], off
	global_load_dwordx4 v[8:11], v[8:9], off
	s_waitcnt vmcnt(2)
	v_fmamk_f32 v13, v13, 0x3b000000, v203
	v_cmp_gt_f32_e32 vcc, s71, v13
	v_mul_f32_e32 v3, 0x4b800000, v13
	s_nop 0
	v_cndmask_b32_e32 v13, v13, v3, vcc
	v_rsq_f32_e32 v13, v13
	s_nop 0
	v_mul_f32_e32 v3, 0x45800000, v13
	v_cndmask_b32_e32 v12, v13, v3, vcc
	s_mov_b64 s[2:3], 0x7fffff
	v_cmp_lt_u64_e32 vcc, s[2:3], v[0:1]
	s_or_b64 s[24:25], vcc, s[24:25]
	s_waitcnt vmcnt(1)
	v_lshlrev_b32_e32 v20, 16, v4
	v_and_b32_e32 v21, 0xffff0000, v4
	v_pk_mul_f32 v[20:21], v[12:13], v[20:21] op_sel_hi:[0,1]
	s_waitcnt vmcnt(0)
	v_lshlrev_b32_e32 v16, 16, v8
	v_mul_f32_e32 v3, 0xbfb8aa3b, v16
	v_exp_f32_e32 v3, v3
	v_and_b32_e32 v17, 0xffff0000, v8
	v_lshlrev_b32_e32 v8, 16, v9
	v_and_b32_e32 v9, 0xffff0000, v9
	v_add_f32_e32 v3, 1.0, v3
	v_rcp_f32_e32 v18, v3
	v_mul_f32_e32 v3, 0xbfb8aa3b, v17
	v_exp_f32_e32 v3, v3
	s_nop 0
	v_add_f32_e32 v3, 1.0, v3
	v_rcp_f32_e32 v19, v3
	v_mul_f32_e32 v3, 0xbfb8aa3b, v8
	v_exp_f32_e32 v3, v3
	v_pk_mul_f32 v[16:17], v[18:19], v[16:17]
	s_nop 0
	v_pk_mul_f32 v[16:17], v[20:21], v[16:17]
	v_add_f32_e32 v3, 1.0, v3
	v_cvt_pk_bf16_f32 v4, v16, v17
	v_rcp_f32_e32 v16, v3
	v_mul_f32_e32 v3, 0xbfb8aa3b, v9
	v_exp_f32_e32 v3, v3
	v_lshlrev_b32_e32 v18, 16, v5
	v_and_b32_e32 v19, 0xffff0000, v5
	v_pk_mul_f32 v[18:19], v[12:13], v[18:19] op_sel_hi:[0,1]
	v_add_f32_e32 v3, 1.0, v3
	v_rcp_f32_e32 v17, v3
	s_nop 0
	v_pk_mul_f32 v[8:9], v[16:17], v[8:9]
	s_nop 0
	v_pk_mul_f32 v[8:9], v[18:19], v[8:9]
	v_lshlrev_b32_e32 v18, 16, v6
	v_cvt_pk_bf16_f32 v5, v8, v9
	v_lshlrev_b32_e32 v8, 16, v10
	v_mul_f32_e32 v3, 0xbfb8aa3b, v8
	v_exp_f32_e32 v3, v3
	v_and_b32_e32 v9, 0xffff0000, v10
	v_and_b32_e32 v19, 0xffff0000, v6
	v_pk_mul_f32 v[18:19], v[12:13], v[18:19] op_sel_hi:[0,1]
	v_add_f32_e32 v3, 1.0, v3
	v_rcp_f32_e32 v16, v3
	v_mul_f32_e32 v3, 0xbfb8aa3b, v9
	v_exp_f32_e32 v3, v3
	s_nop 0
	v_add_f32_e32 v3, 1.0, v3
	v_rcp_f32_e32 v17, v3
	s_nop 0
	v_pk_mul_f32 v[8:9], v[16:17], v[8:9]
	s_nop 0
	v_pk_mul_f32 v[8:9], v[18:19], v[8:9]
	v_lshlrev_b32_e32 v16, 16, v7
	v_cvt_pk_bf16_f32 v6, v8, v9
	v_lshlrev_b32_e32 v8, 16, v11
	v_mul_f32_e32 v3, 0xbfb8aa3b, v8
	v_exp_f32_e32 v3, v3
	v_and_b32_e32 v9, 0xffff0000, v11
	v_and_b32_e32 v17, 0xffff0000, v7
	v_pk_mul_f32 v[12:13], v[12:13], v[16:17] op_sel_hi:[0,1]
	v_add_f32_e32 v3, 1.0, v3
	v_rcp_f32_e32 v10, v3
	v_mul_f32_e32 v3, 0xbfb8aa3b, v9
	v_exp_f32_e32 v3, v3
	s_nop 0
	v_add_f32_e32 v3, 1.0, v3
	v_rcp_f32_e32 v11, v3
	s_nop 0
	v_pk_mul_f32 v[8:9], v[10:11], v[8:9]
	s_nop 0
	v_pk_mul_f32 v[8:9], v[12:13], v[8:9]
	s_nop 0
	v_cvt_pk_bf16_f32 v7, v8, v9
	global_store_dwordx4 v[14:15], v[4:7], off
	s_andn2_b64 exec, exec, s[24:25]
	s_cbranch_execnz .LBB0_44

; __device__ __forceinline__ int opaque_tid() { int t = threadIdx.x; asm volatile("" : "+v"(t)); return t; }
; __device__ __forceinline__ void pass_ret_scan(const Params& P) {
;     const int tidx = opaque_tid();
;     float* st = (float*)(P.ws + WS_RST);
;     for (size_t i = GTID; i < (size_t)64 * 16384; i += GTHREADS) {
;         const int hd = (int)(i >> 14), e = (int)(i & 16383), h = hd >> 3, dvs = hd & 7;
;         const float gc = exp2f(1024.f * ret_log2_gamma(h));
;         float s = 0.f;
; #pragma unroll 8
;         for (int sc = 0; sc < 16; ++sc) { const size_t u = ((size_t)h * 16 + sc) * 8 + dvs; const float loc = st[u * 16384 + e]; st[u * 16384 + e] = s; s = gc * s + loc; }
;     }
; }
.LBB0_60:
	v_lshl_add_u64 v[8:9], v[2:3], 0, s[14:15]
	s_add_u32 s14, s14, 0x400000
	s_addc_u32 s15, s15, 0
	v_add_co_u32_e32 v10, vcc, 0x39c00000, v8
	s_nop 1
	v_addc_co_u32_e32 v11, vcc, 0, v9, vcc
	global_load_dword v12, v[10:11], off
	v_add_co_u32_e32 v10, vcc, 0x39c80000, v8
	s_nop 1
	v_addc_co_u32_e32 v11, vcc, 0, v9, vcc
	global_load_dword v13, v[10:11], off
	v_add_co_u32_e32 v10, vcc, 0x39d00000, v8
	s_nop 1
	v_addc_co_u32_e32 v11, vcc, 0, v9, vcc
	global_load_dword v14, v[10:11], off
	v_add_co_u32_e32 v10, vcc, 0x39d80000, v8
	s_nop 1
	v_addc_co_u32_e32 v11, vcc, 0, v9, vcc
	global_load_dword v15, v[10:11], off
	v_add_co_u32_e32 v10, vcc, 0x39e00000, v8
	s_nop 1
	v_addc_co_u32_e32 v11, vcc, 0, v9, vcc
	global_load_dword v16, v[10:11], off
	v_add_co_u32_e32 v10, vcc, 0x39e80000, v8
	s_nop 1
	v_addc_co_u32_e32 v11, vcc, 0, v9, vcc
	global_load_dword v17, v[10:11], off
	v_add_co_u32_e32 v10, vcc, 0x39f00000, v8
	s_nop 1
	v_addc_co_u32_e32 v11, vcc, 0, v9, vcc
	global_load_dword v18, v[10:11], off
	v_add_co_u32_e32 v10, vcc, 0x39f80000, v8
	s_nop 1
	v_addc_co_u32_e32 v11, vcc, 0, v9, vcc
	global_load_dword v19, v[10:11], off
	v_add_co_u32_e32 v10, vcc, 0x39c00000, v8
	s_nop 1
	v_addc_co_u32_e32 v11, vcc, 0, v9, vcc
	s_waitcnt vmcnt(7)
	global_store_dword v[10:11], v6, off
	v_fmac_f32_e32 v12, v5, v6
	v_add_co_u32_e32 v10, vcc, 0x39c80000, v8
	s_nop 1
	v_addc_co_u32_e32 v11, vcc, 0, v9, vcc
	s_waitcnt vmcnt(7)
	global_store_dword v[10:11], v12, off
	v_fmac_f32_e32 v13, v5, v12
	v_add_co_u32_e32 v10, vcc, 0x39d00000, v8
	s_nop 1
	v_addc_co_u32_e32 v11, vcc, 0, v9, vcc
	s_waitcnt vmcnt(7)
	global_store_dword v[10:11], v13, off
	v_fmac_f32_e32 v14, v5, v13
	v_add_co_u32_e32 v10, vcc, 0x39d80000, v8
	s_nop 1
	v_addc_co_u32_e32 v11, vcc, 0, v9, vcc
	s_waitcnt vmcnt(7)
	global_store_dword v[10:11], v14, off
	v_fmac_f32_e32 v15, v5, v14
	v_add_co_u32_e32 v10, vcc, 0x39e00000, v8
	s_nop 1
	v_addc_co_u32_e32 v11, vcc, 0, v9, vcc
	s_waitcnt vmcnt(7)
	global_store_dword v[10:11], v15, off
	v_fmac_f32_e32 v16, v5, v15
	v_add_co_u32_e32 v10, vcc, 0x39e80000, v8
	s_nop 1
	v_addc_co_u32_e32 v11, vcc, 0, v9, vcc
	s_waitcnt vmcnt(7)
	global_store_dword v[10:11], v16, off
	v_fmac_f32_e32 v17, v5, v16
	v_add_co_u32_e32 v10, vcc, 0x39f00000, v8
	s_nop 1
	v_addc_co_u32_e32 v11, vcc, 0, v9, vcc
	s_waitcnt vmcnt(7)
	global_store_dword v[10:11], v17, off
	v_fmac_f32_e32 v18, v5, v17
	v_add_co_u32_e32 v10, vcc, 0x39f80000, v8
	s_nop 1
	v_addc_co_u32_e32 v11, vcc, 0, v9, vcc
	s_waitcnt vmcnt(7)
	global_store_dword v[10:11], v18, off
	v_fmac_f32_e32 v19, v5, v18
	v_mov_b32_e32 v6, v19
	s_cmp_eq_u32 s14, 0x800000
	s_cbranch_scc0 .LBB0_60
	v_lshl_add_u64 v[0:1], v[0:1], 0, s[68:69]
	s_mov_b64 s[2:3], 0xfffff
	v_cmp_lt_u64_e32 vcc, s[2:3], v[0:1]
	v_readlane_b32 s2, v252, 45
	s_or_b64 s[6:7], vcc, s[6:7]
	s_nop 0
	v_add_u16_e32 v4, s2, v4
	s_andn2_b64 exec, exec, s[6:7]
	s_cbranch_execnz .LBB0_59

; __device__ __forceinline__ int opaque_tid() { int t = threadIdx.x; asm volatile("" : "+v"(t)); return t; }
; __device__ __forceinline__ void pass_hgrn_scan(const Params& P) {
;     const int tidx = opaque_tid();
;     float* st = (float*)(P.ws + WS_HST); const float* D = (const float*)(P.ws + WS_HGD);
;     for (size_t i = GTID; i < (size_t)16 * 16384; i += GTHREADS) {
;         const int bh = (int)(i >> 14), e = (int)(i & 16383), k = e >> 7;
;         float s = 0.f;
; #pragma unroll 8
;         for (int sc = 0; sc < 64; ++sc) { const size_t u = (size_t)bh * 64 + sc; const float loc = st[u * 16384 + e]; st[u * 16384 + e] = s; s = D[u * 128 + k] * s + loc; }
;     }
; }
.LBB0_215:
	v_lshl_add_u64 v[8:9], s[92:93], 0, v[2:3]
	v_lshl_add_u64 v[10:11], s[92:93], 0, v[4:5]
	s_waitcnt lgkmcnt(0)
	v_add_co_u32_e32 v10, vcc, 0x200000, v10
	s_nop 1
	v_addc_co_u32_e32 v11, vcc, 0, v11, vcc
	s_mov_b64 s[10:11], 0x1000
	s_add_i32 s2, s2, -8
	v_lshl_add_u64 v[4:5], v[4:5], 0, s[10:11]
	v_lshl_add_u64 v[2:3], v[2:3], 0, s[12:13]
	global_load_dword v28, v[10:11], off
	global_load_dword v29, v[10:11], off offset:512
	global_load_dword v30, v[10:11], off offset:1024
	global_load_dword v31, v[10:11], off offset:1536
	global_load_dword v32, v[10:11], off offset:2048
	global_load_dword v33, v[10:11], off offset:2560
	global_load_dword v34, v[10:11], off offset:3072
	global_load_dword v35, v[10:11], off offset:3584
	v_add_co_u32_e32 v12, vcc, 0x36000000, v8
	s_nop 1
	v_addc_co_u32_e32 v13, vcc, 0, v9, vcc
	global_load_dword v20, v[12:13], off
	v_add_co_u32_e32 v12, vcc, 0x36010000, v8
	s_nop 1
	v_addc_co_u32_e32 v13, vcc, 0, v9, vcc
	global_load_dword v21, v[12:13], off
	v_add_co_u32_e32 v12, vcc, 0x36020000, v8
	s_nop 1
	v_addc_co_u32_e32 v13, vcc, 0, v9, vcc
	global_load_dword v22, v[12:13], off
	v_add_co_u32_e32 v12, vcc, 0x36030000, v8
	s_nop 1
	v_addc_co_u32_e32 v13, vcc, 0, v9, vcc
	global_load_dword v23, v[12:13], off
	v_add_co_u32_e32 v12, vcc, 0x36040000, v8
	s_nop 1
	v_addc_co_u32_e32 v13, vcc, 0, v9, vcc
	global_load_dword v24, v[12:13], off
	v_add_co_u32_e32 v12, vcc, 0x36050000, v8
	s_nop 1
	v_addc_co_u32_e32 v13, vcc, 0, v9, vcc
	global_load_dword v25, v[12:13], off
	v_add_co_u32_e32 v12, vcc, 0x36060000, v8
	s_nop 1
	v_addc_co_u32_e32 v13, vcc, 0, v9, vcc
	global_load_dword v26, v[12:13], off
	v_add_co_u32_e32 v12, vcc, 0x36070000, v8
	s_nop 1
	v_addc_co_u32_e32 v13, vcc, 0, v9, vcc
	global_load_dword v27, v[12:13], off
	v_add_co_u32_e32 v12, vcc, 0x36000000, v8
	s_nop 1
	v_addc_co_u32_e32 v13, vcc, 0, v9, vcc
	s_waitcnt vmcnt(7)
	global_store_dword v[12:13], v7, off
	v_fmac_f32_e32 v20, v7, v28
	v_add_co_u32_e32 v12, vcc, 0x36010000, v8
	s_nop 1
	v_addc_co_u32_e32 v13, vcc, 0, v9, vcc
	s_waitcnt vmcnt(7)
	global_store_dword v[12:13], v20, off
	v_fmac_f32_e32 v21, v20, v29
	v_add_co_u32_e32 v12, vcc, 0x36020000, v8
	s_nop 1
	v_addc_co_u32_e32 v13, vcc, 0, v9, vcc
	s_waitcnt vmcnt(7)
	global_store_dword v[12:13], v21, off
	v_fmac_f32_e32 v22, v21, v30
	v_add_co_u32_e32 v12, vcc, 0x36030000, v8
	s_nop 1
	v_addc_co_u32_e32 v13, vcc, 0, v9, vcc
	s_waitcnt vmcnt(7)
	global_store_dword v[12:13], v22, off
	v_fmac_f32_e32 v23, v22, v31
	v_add_co_u32_e32 v12, vcc, 0x36040000, v8
	s_nop 1
	v_addc_co_u32_e32 v13, vcc, 0, v9, vcc
	s_waitcnt vmcnt(7)
	global_store_dword v[12:13], v23, off
	v_fmac_f32_e32 v24, v23, v32
	v_add_co_u32_e32 v12, vcc, 0x36050000, v8
	s_nop 1
	v_addc_co_u32_e32 v13, vcc, 0, v9, vcc
	s_waitcnt vmcnt(7)
	global_store_dword v[12:13], v24, off
	v_fmac_f32_e32 v25, v24, v33
	v_add_co_u32_e32 v12, vcc, 0x36060000, v8
	s_nop 1
	v_addc_co_u32_e32 v13, vcc, 0, v9, vcc
	s_waitcnt vmcnt(7)
	global_store_dword v[12:13], v25, off
	v_fmac_f32_e32 v26, v25, v34
	v_add_co_u32_e32 v12, vcc, 0x36070000, v8
	s_nop 1
	v_addc_co_u32_e32 v13, vcc, 0, v9, vcc
	s_waitcnt vmcnt(7)
	global_store_dword v[12:13], v26, off
	v_fmac_f32_e32 v27, v26, v35
	v_mov_b32_e32 v7, v27
	s_cmp_eq_u32 s2, 0
	s_cbranch_scc0 .LBB0_215
	v_lshl_add_u64 v[0:1], v[0:1], 0, s[68:69]
	v_cmp_lt_u64_e32 vcc, s[90:91], v[0:1]
	v_readlane_b32 s2, v252, 45
	s_or_b64 s[6:7], vcc, s[6:7]
	s_nop 0
	v_add_u16_e32 v6, s2, v6
	s_andn2_b64 exec, exec, s[6:7]
	s_cbranch_execnz .LBB0_214
